# nbr attention bias: straight-line ds_read2 table reads instead of 16 exec-masked serialized reads
# speedup vs baseline: 1.0097x; 1.0097x over previous
; #define ATT_LAS __attribute__((address_space(3)))
; __device__ __forceinline__ int crow(int r, int hi) { return (r & 3) + 8 * (r >> 2) + 4 * hi; }
; __device__ __forceinline__ void attn_unit(int uv, const float* sink_l, const bf16_t* P, bf16_t* Y, ATT_LAS unsigned char* lds, const float* rpb_l, const float* qn_l, const float* kn_l) {
;     ...
;                 for (int d0 = 0; d0 < 4; ++d0) {
;                     const bf16x8 k0 = *(const ATT_LAS bf16x8*)(Kb + kfrag + d0 * 2048);
;                     const bf16x8 k1 = *(const ATT_LAS bf16x8*)(Kb + kfrag + d0 * 2048 + 512);
;                     p0 = __builtin_amdgcn_mfma_f32_32x32x16_bf16(k0, qf[d0], p0, 0, 0, 0);
;                     p1 = __builtin_amdgcn_mfma_f32_32x32x16_bf16(k1, qf[d0], p1, 0, 0, 0);
;                 }
;                 if (a.mode == 1) { const int dq = tl * 64 - (qw + r32);
; #pragma unroll
;                     for (int r = 0; r < 16; ++r) { const int d = dq + crow(r, hi); if (d > 128 || d < -128) p0[r] = NEGF; if (d + 32 > 128 || d + 32 < -128) p1[r] = NEGF; } }
;                 else { const int qc = 32 * (wid & 1) + r32, cs = clampi(qc - 8, 0, 48); const ATT_LAS float* trow = tbl + (tl - qr + 7) * 31 + 15 - qc;
; #pragma unroll
;                     for (int r = 0; r < 16; ++r) { const int kcl = crow(r, hi);
;                         const float b0 = trow[kcl], b1 = trow[kcl + 32];
;                         p0[r] = ((unsigned)(kcl - cs) < 16u) ? p0[r] + b0 : NEGF;
;                         p1[r] = ((unsigned)(kcl + 32 - cs) < 16u) ? p1[r] + b1 : NEGF; } }
.LBB0_657:
	s_lshl_b32 s86, s72, 13
	v_add_u32_e32 v40, s86, v221
	ds_read_b128 v[32:35], v40
	ds_read_b128 v[36:39], v40 offset:512
	s_mov_b64 s[84:85], -1
	s_and_b64 vcc, exec, s[2:3]
	s_waitcnt lgkmcnt(1)
	v_mfma_f32_32x32x16_bf16 v[80:95], v[32:35], v[96:99], 0
	s_waitcnt lgkmcnt(0)
	v_mfma_f32_32x32x16_bf16 v[48:63], v[36:39], v[96:99], 0
	ds_read_b128 v[32:35], v40 offset:2048
	ds_read_b128 v[36:39], v40 offset:2560
	s_waitcnt lgkmcnt(1)
	v_mfma_f32_32x32x16_bf16 v[80:95], v[32:35], v[100:103], v[80:95]
	s_waitcnt lgkmcnt(0)
	v_mfma_f32_32x32x16_bf16 v[48:63], v[36:39], v[100:103], v[48:63]
	ds_read_b128 v[32:35], v40 offset:4096
	ds_read_b128 v[36:39], v40 offset:4608
	s_waitcnt lgkmcnt(1)
	v_mfma_f32_32x32x16_bf16 v[80:95], v[32:35], v[104:107], v[80:95]
	s_waitcnt lgkmcnt(0)
	v_mfma_f32_32x32x16_bf16 v[48:63], v[36:39], v[104:107], v[48:63]
	ds_read_b128 v[32:35], v40 offset:6144
	ds_read_b128 v[36:39], v40 offset:6656
	s_waitcnt lgkmcnt(1)
	v_mfma_f32_32x32x16_bf16 v[80:95], v[32:35], v[108:111], v[80:95]
	s_waitcnt lgkmcnt(0)
	v_mfma_f32_32x32x16_bf16 v[48:63], v[36:39], v[108:111], v[48:63]
	s_cbranch_vccz .LBB0_691
	ds_read2_b32 v[64:65], v127 offset0:32 offset1:33
	ds_read2_b32 v[66:67], v127 offset0:34 offset1:35
	ds_read2_b32 v[68:69], v127 offset0:40 offset1:41
	ds_read2_b32 v[70:71], v127 offset0:42 offset1:43
	ds_read2_b32 v[72:73], v127 offset0:48 offset1:49
	ds_read2_b32 v[74:75], v127 offset0:50 offset1:51
	ds_read2_b32 v[76:77], v127 offset0:56 offset1:57
	ds_read2_b32 v[78:79], v127 offset0:58 offset1:59
	ds_read2_b32 v[32:33], v127 offset1:1
	ds_read2_b32 v[34:35], v127 offset0:2 offset1:3
	ds_read2_b32 v[36:37], v127 offset0:8 offset1:9
	ds_read2_b32 v[38:39], v127 offset0:10 offset1:11
	ds_read2_b32 v[40:41], v127 offset0:16 offset1:17
	ds_read2_b32 v[42:43], v127 offset0:18 offset1:19
	ds_read2_b32 v[44:45], v127 offset0:24 offset1:25
	s_waitcnt lgkmcnt(14)
	ds_read2_b32 v[46:47], v127 offset0:26 offset1:27
	v_add_f32_e32 v64, v48, v64
	v_add_f32_e32 v65, v49, v65
	v_cndmask_b32_e64 v64, v216, v64, s[68:69]
	v_cndmask_b32_e64 v65, v216, v65, s[8:9]
	s_waitcnt lgkmcnt(14)
	v_add_f32_e32 v66, v50, v66
	v_add_f32_e32 v67, v51, v67
	v_cndmask_b32_e64 v66, v216, v66, s[12:13]
	v_cndmask_b32_e64 v67, v216, v67, s[16:17]
	s_waitcnt lgkmcnt(13)
	v_add_f32_e32 v68, v52, v68
	v_add_f32_e32 v69, v53, v69
	v_cndmask_b32_e64 v68, v216, v68, s[20:21]
	v_cndmask_b32_e64 v69, v216, v69, s[24:25]
	s_waitcnt lgkmcnt(12)
	v_add_f32_e32 v70, v54, v70
	v_add_f32_e32 v71, v55, v71
	v_cndmask_b32_e64 v70, v216, v70, s[28:29]
	v_cndmask_b32_e64 v71, v216, v71, s[94:95]
	s_waitcnt lgkmcnt(11)
	v_add_f32_e32 v72, v56, v72
	v_add_f32_e32 v73, v57, v73
	v_cndmask_b32_e64 v72, v216, v72, s[38:39]
	v_cndmask_b32_e64 v73, v216, v73, s[42:43]
	s_waitcnt lgkmcnt(10)
	v_add_f32_e32 v74, v58, v74
	v_add_f32_e32 v75, v59, v75
	v_cndmask_b32_e64 v74, v216, v74, s[46:47]
	v_cndmask_b32_e64 v75, v216, v75, s[50:51]
	s_waitcnt lgkmcnt(9)
	v_add_f32_e32 v76, v60, v76
	v_add_f32_e32 v77, v61, v77
	v_cndmask_b32_e64 v76, v216, v76, s[54:55]
	v_cndmask_b32_e64 v77, v216, v77, s[58:59]
	s_waitcnt lgkmcnt(8)
	v_add_f32_e32 v78, v62, v78
	v_add_f32_e32 v79, v63, v79
	v_cndmask_b32_e64 v78, v216, v78, s[62:63]
	v_cndmask_b32_e64 v79, v216, v79, s[66:67]
	s_waitcnt lgkmcnt(7)
	v_add_f32_e32 v32, v80, v32
	v_add_f32_e32 v33, v81, v33
	v_cndmask_b32_e64 v32, v216, v32, s[0:1]
	v_cndmask_b32_e64 v33, v216, v33, s[4:5]
	s_waitcnt lgkmcnt(6)
	v_add_f32_e32 v34, v82, v34
	v_add_f32_e32 v35, v83, v35
	v_cndmask_b32_e64 v34, v216, v34, s[10:11]
	v_cndmask_b32_e64 v35, v216, v35, s[14:15]
	s_waitcnt lgkmcnt(5)
	v_add_f32_e32 v36, v84, v36
	v_add_f32_e32 v37, v85, v37
	v_cndmask_b32_e64 v36, v216, v36, s[18:19]
	v_cndmask_b32_e64 v37, v216, v37, s[22:23]
	s_waitcnt lgkmcnt(4)
	v_add_f32_e32 v38, v86, v38
	v_add_f32_e32 v39, v87, v39
	v_cndmask_b32_e64 v38, v216, v38, s[26:27]
	v_cndmask_b32_e64 v39, v216, v39, s[30:31]
	s_waitcnt lgkmcnt(3)
	v_add_f32_e32 v40, v88, v40
	v_add_f32_e32 v41, v89, v41
	v_cndmask_b32_e64 v40, v216, v40, s[76:77]
	v_cndmask_b32_e64 v41, v216, v41, s[40:41]
	s_waitcnt lgkmcnt(2)
	v_add_f32_e32 v42, v90, v42
	v_add_f32_e32 v43, v91, v43
	v_cndmask_b32_e64 v42, v216, v42, s[44:45]
	v_cndmask_b32_e64 v43, v216, v43, s[48:49]
	s_waitcnt lgkmcnt(1)
	v_add_f32_e32 v44, v92, v44
	v_add_f32_e32 v45, v93, v45
	v_cndmask_b32_e64 v44, v216, v44, s[52:53]
	v_cndmask_b32_e64 v45, v216, v45, s[56:57]
	s_waitcnt lgkmcnt(0)
	v_add_f32_e32 v46, v94, v46
	v_add_f32_e32 v47, v95, v47
	v_cndmask_b32_e64 v46, v216, v46, s[60:61]
	v_cndmask_b32_e64 v47, v216, v47, s[64:65]
	s_mov_b64 s[84:85], 0
